# diff map prologue fetches Q, tile 0 and tile 1 together; NSA top-k radix select with the eight threshold searches interleaved on private scalar registers
# baseline (speedup 1.0000x reference)
; template <int DV, bool HAS_V>
; DI void kv_gload(KVStage<DV>& st, const bf16_t* __restrict__ Kb, const bf16_t* __restrict__ VTb, int ldv, int key0) {
;     const int tid = threadIdx.x;
;     st.k[0] = *(const u32x4*)(Kb + (size_t)(key0 + (tid >> 3)) * 64 + (tid & 7) * 8);
;     if (HAS_V) {
; #pragma unroll
;         for (int i = 0; i < DV / 64; ++i) { const int c = tid + 512 * i; st.v[i] = *(const u32x4*)(VTb + (size_t)(key0 >> 6) * (DV * 64) + c * 8); }
;     }
; }
;     ...
;         bf16x8 qf[4];
; #pragma unroll
;         for (int s = 0; s < 4; ++s) qf[s] = *(const bf16x8*)(Qb + (size_t)qpos * 64 + s * 16 + h * 8);
; #pragma unroll
;         for (int s = 0; s < 4; ++s) asm volatile("" : "+v"(qf[s]));
;         f32x16 o[4];
; #pragma unroll
;         for (int dt = 0; dt < 4; ++dt)
; #pragma unroll
;             for (int i = 0; i < 16; ++i) o[dt][i] = 0.f;
;         float m = -1e30f; f32x16 lv;
; #pragma unroll
;         for (int i = 0; i < 16; ++i) lv[i] = 0.f;
;         kv_loop<128, true>(lds, Kb, VTb, 4096, ntl, 0, [](int j) { return j + 1; }, [&](int j, const unsigned char* sb) {
.LBB0_467:
	v_or_b32_e32 v2, s4, v189
	v_lshlrev_b64 v[4:5], 1, v[2:3]
	v_lshl_add_u64 v[6:7], v[174:175], 0, v[4:5]
	global_load_dwordx4 v[130:133], v[6:7], off
	global_load_dwordx4 v[134:137], v[6:7], off offset:32
	global_load_dwordx4 v[138:141], v[6:7], off offset:64
	global_load_dwordx4 v[142:145], v[6:7], off offset:96
	v_lshl_add_u64 v[100:101], s[10:11], 0, v[4:5]
	v_mov_b32_e32 v173, v3
	v_lshl_add_u64 v[4:5], v[100:101], 0, v[170:171]
	v_lshl_add_u64 v[4:5], v[4:5], 0, v[172:173]
	v_mov_b32_e32 v16, v3
	v_mov_b32_e32 v17, v3
	v_mov_b32_e32 v6, v3
	v_mov_b32_e32 v7, v3
	v_mov_b32_e32 v8, v3
	v_mov_b32_e32 v9, v3
	v_mov_b32_e32 v10, v3
	v_mov_b32_e32 v11, v3
	v_mov_b32_e32 v12, v3
	v_mov_b32_e32 v13, v3
	v_mov_b32_e32 v14, v3
	v_mov_b32_e32 v15, v3
	v_mov_b32_e32 v2, v3
	s_xor_b64 s[20:21], s[2:3], -1
	v_mov_b32_e32 v98, 0
	v_mov_b32_e32 v163, 0xf149f2ca
	s_mov_b64 s[2:3], 0
	s_mov_b32 s24, 0
	global_load_dwordx4 v[146:149], v[4:5], off
	global_load_dwordx4 v[150:153], v[164:165], off
	global_load_dwordx4 v[154:157], v[166:167], off
	s_mov_b64 s[56:57], 0x2000
	s_mov_b64 s[58:59], 0x4000
	v_lshl_add_u64 v[226:227], v[4:5], 0, s[56:57]
	global_load_dwordx4 v[214:217], v[226:227], off
	v_lshl_add_u64 v[226:227], v[164:165], 0, s[58:59]
	global_load_dwordx4 v[218:221], v[226:227], off
	v_lshl_add_u64 v[226:227], v[166:167], 0, s[58:59]
	global_load_dwordx4 v[222:225], v[226:227], off

;     ...
;         f32x16 o[4];
; #pragma unroll
;         for (int dt = 0; dt < 4; ++dt)
; #pragma unroll
;             for (int i = 0; i < 16; ++i) o[dt][i] = 0.f;
;         float m = -1e30f; f32x16 lv;
; #pragma unroll
;         for (int i = 0; i < 16; ++i) lv[i] = 0.f;
;         kv_loop<128, true>(lds, Kb, VTb, 4096, ntl, 0, [](int j) { return j + 1; }, [&](int j, const unsigned char* sb) {
;             const int k0 = j * 64;
	v_mov_b32_e32 v4, v3
	v_mov_b32_e32 v5, v3
	v_mov_b64_e32 v[32:33], v[16:17]
	v_mov_b64_e32 v[48:49], v[16:17]
	v_mov_b64_e32 v[64:65], v[16:17]
	v_mov_b64_e32 v[80:81], v[16:17]
	v_mov_b64_e32 v[96:97], v[16:17]
	v_mov_b64_e32 v[30:31], v[14:15]
	v_mov_b64_e32 v[28:29], v[12:13]
	v_mov_b64_e32 v[26:27], v[10:11]
	v_mov_b64_e32 v[24:25], v[8:9]
	v_mov_b64_e32 v[22:23], v[6:7]
	v_mov_b64_e32 v[20:21], v[4:5]
	v_mov_b64_e32 v[18:19], v[2:3]
	v_mov_b64_e32 v[46:47], v[14:15]
	v_mov_b64_e32 v[44:45], v[12:13]
	v_mov_b64_e32 v[42:43], v[10:11]
	v_mov_b64_e32 v[40:41], v[8:9]
	v_mov_b64_e32 v[38:39], v[6:7]
	v_mov_b64_e32 v[36:37], v[4:5]
	v_mov_b64_e32 v[34:35], v[2:3]
	v_mov_b64_e32 v[62:63], v[14:15]
	v_mov_b64_e32 v[60:61], v[12:13]
	v_mov_b64_e32 v[58:59], v[10:11]
	v_mov_b64_e32 v[56:57], v[8:9]
	v_mov_b64_e32 v[54:55], v[6:7]
	v_mov_b64_e32 v[52:53], v[4:5]
	v_mov_b64_e32 v[50:51], v[2:3]
	v_mov_b64_e32 v[78:79], v[14:15]
	v_mov_b64_e32 v[76:77], v[12:13]
	v_mov_b64_e32 v[74:75], v[10:11]
	v_mov_b64_e32 v[72:73], v[8:9]
	v_mov_b64_e32 v[70:71], v[6:7]
	v_mov_b64_e32 v[68:69], v[4:5]
	v_mov_b64_e32 v[66:67], v[2:3]
	v_mov_b64_e32 v[94:95], v[14:15]
	v_mov_b64_e32 v[92:93], v[12:13]
	v_mov_b64_e32 v[90:91], v[10:11]
	v_mov_b64_e32 v[88:89], v[8:9]
	v_mov_b64_e32 v[86:87], v[6:7]
	v_mov_b64_e32 v[84:85], v[4:5]
	v_mov_b64_e32 v[82:83], v[2:3]
	v_lshl_add_u64 v[4:5], v[100:101], 0, v[172:173]
	s_waitcnt vmcnt(2)
	ds_write_b128 v198, v[146:149]
	s_waitcnt vmcnt(1)
	ds_write2_b64 v182, v[150:151], v[152:153] offset0:128 offset1:130
	s_waitcnt vmcnt(0)
	ds_write2_b64 v183, v[154:155], v[156:157] offset0:128 offset1:130
	s_waitcnt lgkmcnt(0)
	s_barrier
	v_readfirstlane_b32 s58, v188
	v_readfirstlane_b32 s59, v186
	s_add_i32 s60, s59, 31
	s_mov_b32 s61, 0
	s_movk_i32 s62, 0x6c00
	s_mov_b32 s63, 0xd800

; template <int DV, bool HAS_V>
; DI void kv_sstore(const KVStage<DV>& st, unsigned char* buf) {
;     const int tid = threadIdx.x;
;     *(u32x4*)(buf + (tid >> 3) * KP + (tid & 7) * 16) = st.k[0];
;     if (HAS_V) {
; #pragma unroll
;         for (int i = 0; i < DV / 64; ++i) {
;             const int c = tid + 512 * i, kc = c & 7; unsigned char* q = buf + KT_BYTES + (c >> 3) * VP + (kc >> 1) * 32 + (kc & 1) * 8;
;             u32x2 lo, hi; lo.x = st.v[i].x; lo.y = st.v[i].y; hi.x = st.v[i].z; hi.y = st.v[i].w;
;             *(u32x2*)q = lo; *(u32x2*)(q + 16) = hi;
;         }
;     }
; }
	v_add3_u32 v2, s62, v159, v195
	ds_write_b128 v2, v[214:217]
	v_add3_u32 v2, s62, v196, v197
	v_add_u32_e32 v7, v2, v159
	v_add_u32_e32 v2, v2, v180
	v_add_u32_e32 v7, 0x2000, v7
	v_add_u32_e32 v2, 0x2000, v2
	ds_write2_b64 v7, v[218:219], v[220:221] offset0:128 offset1:130
	ds_write2_b64 v2, v[222:223], v[224:225] offset0:128 offset1:130

; template <int DV, bool HAS_V>
; DI void kv_gload(KVStage<DV>& st, const bf16_t* __restrict__ Kb, const bf16_t* __restrict__ VTb, int ldv, int key0) {
;     const int tid = threadIdx.x;
;     st.k[0] = *(const u32x4*)(Kb + (size_t)(key0 + (tid >> 3)) * 64 + (tid & 7) * 8);
;     if (HAS_V) {
; #pragma unroll
;         for (int i = 0; i < DV / 64; ++i) { const int c = tid + 512 * i; st.v[i] = *(const u32x4*)(VTb + (size_t)(key0 >> 6) * (DV * 64) + c * 8); }
;     }
; }
	s_mov_b32 s24, 2
	s_lshl_b32 s66, s24, 6
	v_add_u32_e32 v8, s66, v187
	v_mov_b32_e32 v9, v3
	v_lshlrev_b64 v[8:9], 7, v[8:9]
	v_lshl_add_u64 v[8:9], v[4:5], 0, v[8:9]
	global_load_dwordx4 v[146:149], v[8:9], off
	s_lshl_b32 s66, s24, 14
	s_mov_b32 s67, 0
	v_lshl_add_u64 v[10:11], v[164:165], 0, s[66:67]
	global_load_dwordx4 v[150:153], v[10:11], off
	s_add_u32 s66, s66, 0x2000
	v_lshl_add_u64 v[10:11], v[164:165], 0, s[66:67]
	global_load_dwordx4 v[154:157], v[10:11], off

; #define MFMA(a, b, c) __builtin_amdgcn_mfma_f32_32x32x16_bf16((a), (b), (c), 0, 0, 0)
; DI void attn_scores(const unsigned char* kb, const bf16x8 (&qf)[4], int r, int h, f32x16& s0, f32x16& s1) {
; #pragma unroll
;     for (int i = 0; i < 16; ++i) { s0[i] = 0.f; s1[i] = 0.f; }
; #pragma unroll
;     for (int s = 0; s < 4; ++s) {
;         const bf16x8 k0 = *(const bf16x8*)(kb + r * KP + s * 32 + h * 16);
;         const bf16x8 k1 = *(const bf16x8*)(kb + (32 + r) * KP + s * 32 + h * 16);
;         s0 = MFMA(k0, qf[s], s0); s1 = MFMA(k1, qf[s], s1);
;     }
; }
	v_add3_u32 v7, s61, v191, v168
	ds_read_b128 v[214:217], v7 offset:0
	ds_read_b128 v[218:221], v7 offset:4608
	ds_read_b128 v[222:225], v7 offset:32
	ds_read_b128 v[226:229], v7 offset:4640
	ds_read_b128 v[230:233], v7 offset:64
	ds_read_b128 v[234:237], v7 offset:4672
	s_waitcnt lgkmcnt(5)
	v_mfma_f32_32x32x16_bf16 v[114:129], v[214:217], v[130:133], 0
	ds_read_b128 v[214:217], v7 offset:96
	s_waitcnt lgkmcnt(5)
	v_mfma_f32_32x32x16_bf16 v[98:113], v[218:221], v[130:133], 0
	ds_read_b128 v[218:221], v7 offset:4704
	s_waitcnt lgkmcnt(5)
	v_mfma_f32_32x32x16_bf16 v[114:129], v[222:225], v[134:137], v[114:129]
	s_waitcnt lgkmcnt(4)
	v_mfma_f32_32x32x16_bf16 v[98:113], v[226:229], v[134:137], v[98:113]
	s_waitcnt lgkmcnt(3)
	v_mfma_f32_32x32x16_bf16 v[114:129], v[230:233], v[138:141], v[114:129]
	s_waitcnt lgkmcnt(2)
	v_mfma_f32_32x32x16_bf16 v[98:113], v[234:237], v[138:141], v[98:113]
	s_waitcnt lgkmcnt(1)
	v_mfma_f32_32x32x16_bf16 v[114:129], v[214:217], v[142:145], v[114:129]
	s_waitcnt lgkmcnt(0)
	v_mfma_f32_32x32x16_bf16 v[98:113], v[218:221], v[142:145], v[98:113]
	s_waitcnt lgkmcnt(0)
	s_mov_b32 s24, 0
	s_cmp_eq_u32 s54, 0
	s_cbranch_scc1 .Ldl_loop
	s_barrier

; #define NEG_INF (-__builtin_inff())
;     ...
;         unsigned uk8[8]; bool val8[8];
;         const int j = lane;
; #pragma unroll
;         for (int qq = 0; qq < 8; ++qq) {
;             const int rr = 8 * w + qq, qp = q0 + rr, cur = qp >> 6;
;             const bool valid = j <= cur;
;             float v = 0.f;
;             if (valid) {
;                 const float* ip = IMPW + ((rr >> 5) * 4 * 32 + (rr & 31)) * 64 + j;
;                 const float* fp = FT + ((rr >> 5) * 4 * 32 + (rr & 31)) * 4 + (j >> 4);
;                 v = ((ip[0] * fp[0] + ip[2048] * fp[128]) + ip[4096] * fp[256]) + ip[6144] * fp[384];
;             }
;             const bool forced = (j == 0) || (j == cur) || (j == cur - 1);
;             const float key = forced ? __builtin_inff() : (valid ? v : NEG_INF);
;             const unsigned kb_ = __float_as_uint(key);
;             uk8[qq] = (kb_ & 0x80000000u) ? ~kb_ : (kb_ | 0x80000000u);
;             val8[qq] = valid;
;         }
;         unsigned thr8[8];
; #pragma unroll
;         for (int qq = 0; qq < 8; ++qq) thr8[qq] = 0u;
; #pragma unroll
;     ...
; #pragma unroll
;             for (int qq = 0; qq < 8; ++qq) {
;                 const unsigned cand = thr8[qq] | (1u << bit);
;                 if (__popcll(__ballot(uk8[qq] >= cand)) >= 16) thr8[qq] = cand;
;             }
;         }
.LBB0_522:
	s_or_b64 exec, exec, s[4:5]
	v_cmp_eq_u32_e64 s[18:19], 0, v84
	v_cmp_eq_u32_e64 s[4:5], v84, v50
	v_add_u32_e32 v35, -1, v50
	s_or_b64 s[2:3], s[18:19], s[4:5]
	v_cmp_eq_u32_e64 s[4:5], v84, v35
	s_or_b64 s[4:5], s[2:3], s[4:5]
	s_nop 0
	v_cndmask_b32_e64 v35, v48, v201, s[4:5]
	v_not_b32_e32 v37, v35
	v_cmp_gt_i32_e64 s[6:7], 0, v35
	v_cndmask_b32_e64 v40, v40, v201, s[4:5]
	v_cndmask_b32_e64 v38, v38, v201, s[4:5]
	v_cndmask_b32_e64 v35, -|v35|, v37, s[6:7]
	v_cndmask_b32_e64 v37, v44, v201, s[4:5]
	v_not_b32_e32 v39, v37
	v_cmp_gt_i32_e64 s[6:7], 0, v37
	v_cndmask_b32_e64 v36, v36, v201, s[4:5]
	v_cndmask_b32_e64 v34, v34, v201, s[4:5]
	v_cndmask_b32_e64 v37, -|v37|, v39, s[6:7]
	v_cndmask_b32_e64 v39, v42, v201, s[4:5]
	v_not_b32_e32 v41, v39
	v_cmp_gt_i32_e64 s[6:7], 0, v39
	s_nop 1
	v_cndmask_b32_e64 v39, -|v39|, v41, s[6:7]
	v_not_b32_e32 v41, v40
	v_cmp_gt_i32_e64 s[6:7], 0, v40
	s_nop 1
	v_cndmask_b32_e64 v40, -|v40|, v41, s[6:7]
	v_not_b32_e32 v41, v38
	v_cmp_gt_i32_e64 s[6:7], 0, v38
	s_nop 1
	v_cndmask_b32_e64 v38, -|v38|, v41, s[6:7]
	v_not_b32_e32 v41, v36
	v_cmp_gt_i32_e64 s[6:7], 0, v36
	s_nop 1
	v_cndmask_b32_e64 v36, -|v36|, v41, s[6:7]
	v_not_b32_e32 v41, v34
	v_cmp_gt_i32_e64 s[6:7], 0, v34
	s_nop 1
	v_cndmask_b32_e64 v41, -|v34|, v41, s[6:7]
	v_cndmask_b32_e64 v34, v46, v201, s[4:5]
	v_not_b32_e32 v42, v34
	v_cmp_gt_i32_e64 s[4:5], 0, v34
	s_nop 1
	v_cndmask_b32_e64 v34, -|v34|, v42, s[4:5]
	v_cmp_gt_i32_e64 s[4:5], 0, v41
	s_bcnt1_i32_b64 s68, s[4:5]
	v_cmp_gt_u64_e64 s[2:3], s[68:69], 15
	s_and_b64 s[2:3], s[2:3], exec
	v_cmp_gt_i32_e64 s[4:5], 0, v36
	s_cselect_b32 s6, 0x80000000, 0
	s_bcnt1_i32_b64 s68, s[4:5]
	v_cmp_gt_u64_e64 s[2:3], s[68:69], 15
	s_and_b64 s[2:3], s[2:3], exec
	v_cmp_gt_i32_e64 s[4:5], 0, v38
	s_cselect_b32 s7, 0x80000000, 0
	s_bcnt1_i32_b64 s68, s[4:5]
	v_cmp_gt_u64_e64 s[2:3], s[68:69], 15
	s_and_b64 s[2:3], s[2:3], exec
	v_cmp_gt_i32_e64 s[4:5], 0, v40
	s_cselect_b32 s8, 0x80000000, 0
	s_bcnt1_i32_b64 s68, s[4:5]
	v_cmp_gt_u64_e64 s[2:3], s[68:69], 15
	s_and_b64 s[2:3], s[2:3], exec
	v_cmp_gt_i32_e64 s[4:5], 0, v39
	s_cselect_b32 s9, 0x80000000, 0
	s_bcnt1_i32_b64 s68, s[4:5]
	v_cmp_gt_u64_e64 s[2:3], s[68:69], 15
	s_and_b64 s[2:3], s[2:3], exec
	v_cmp_gt_i32_e64 s[4:5], 0, v37
	s_cselect_b32 s10, 0x80000000, 0
	s_bcnt1_i32_b64 s68, s[4:5]
	v_cmp_gt_u64_e64 s[2:3], s[68:69], 15
	s_and_b64 s[2:3], s[2:3], exec
	v_cmp_gt_i32_e64 s[4:5], 0, v35
	s_cselect_b32 s11, 0x80000000, 0
	s_bcnt1_i32_b64 s68, s[4:5]
	v_cmp_gt_u64_e64 s[2:3], s[68:69], 15
	s_and_b64 s[2:3], s[2:3], exec
	v_cmp_gt_i32_e64 s[4:5], 0, v34
	s_cselect_b32 s12, 0x80000000, 0
	s_bcnt1_i32_b64 s68, s[4:5]
	v_cmp_gt_u64_e64 s[2:3], s[68:69], 15
	s_and_b64 s[2:3], s[2:3], exec
	s_cselect_b32 s13, 0x80000000, 0
	s_or_b32 s42, s6, 0x40000000
	s_or_b32 s43, s7, 0x40000000
	s_or_b32 s44, s8, 0x40000000
	s_or_b32 s45, s9, 0x40000000
	s_or_b32 s46, s10, 0x40000000
	s_or_b32 s47, s11, 0x40000000
	s_or_b32 s48, s12, 0x40000000
	s_or_b32 s49, s13, 0x40000000
	v_cmp_le_u32_e64 s[20:21], s42, v41
	v_cmp_le_u32_e64 s[22:23], s43, v36
	v_cmp_le_u32_e64 s[24:25], s44, v38
	v_cmp_le_u32_e64 s[26:27], s45, v40
	v_cmp_le_u32_e64 s[28:29], s46, v39
	v_cmp_le_u32_e64 s[30:31], s47, v37
	v_cmp_le_u32_e64 s[34:35], s48, v35
	v_cmp_le_u32_e64 s[36:37], s49, v34
	s_bcnt1_i32_b64 s50, s[20:21]
	s_bcnt1_i32_b64 s51, s[22:23]
	s_bcnt1_i32_b64 s52, s[24:25]
	s_bcnt1_i32_b64 s53, s[26:27]
	s_bcnt1_i32_b64 s54, s[28:29]
	s_bcnt1_i32_b64 s55, s[30:31]
	s_bcnt1_i32_b64 s56, s[34:35]
	s_bcnt1_i32_b64 s57, s[36:37]
	s_cmp_gt_u32 s50, 15
	s_cselect_b32 s6, s42, s6
	s_cmp_gt_u32 s51, 15
	s_cselect_b32 s7, s43, s7
	s_cmp_gt_u32 s52, 15
	s_cselect_b32 s8, s44, s8
	s_cmp_gt_u32 s53, 15
	s_cselect_b32 s9, s45, s9
	s_cmp_gt_u32 s54, 15
	s_cselect_b32 s10, s46, s10
	s_cmp_gt_u32 s55, 15
	s_cselect_b32 s11, s47, s11
	s_cmp_gt_u32 s56, 15
	s_cselect_b32 s12, s48, s12
	s_cmp_gt_u32 s57, 15
	s_cselect_b32 s13, s49, s13
	s_or_b32 s42, s6, 0x20000000
	s_or_b32 s43, s7, 0x20000000
	s_or_b32 s44, s8, 0x20000000
	s_or_b32 s45, s9, 0x20000000
	s_or_b32 s46, s10, 0x20000000
	s_or_b32 s47, s11, 0x20000000
	s_or_b32 s48, s12, 0x20000000
	s_or_b32 s49, s13, 0x20000000
	v_cmp_le_u32_e64 s[20:21], s42, v41
	v_cmp_le_u32_e64 s[22:23], s43, v36
	v_cmp_le_u32_e64 s[24:25], s44, v38
	v_cmp_le_u32_e64 s[26:27], s45, v40
	v_cmp_le_u32_e64 s[28:29], s46, v39
	v_cmp_le_u32_e64 s[30:31], s47, v37
	v_cmp_le_u32_e64 s[34:35], s48, v35
	v_cmp_le_u32_e64 s[36:37], s49, v34
	s_bcnt1_i32_b64 s50, s[20:21]
	s_bcnt1_i32_b64 s51, s[22:23]
	s_bcnt1_i32_b64 s52, s[24:25]
	s_bcnt1_i32_b64 s53, s[26:27]
	s_bcnt1_i32_b64 s54, s[28:29]
	s_bcnt1_i32_b64 s55, s[30:31]
	s_bcnt1_i32_b64 s56, s[34:35]
	s_bcnt1_i32_b64 s57, s[36:37]
	s_cmp_gt_u32 s50, 15
	s_cselect_b32 s6, s42, s6
	s_cmp_gt_u32 s51, 15
	s_cselect_b32 s7, s43, s7
	s_cmp_gt_u32 s52, 15
	s_cselect_b32 s8, s44, s8
	s_cmp_gt_u32 s53, 15
	s_cselect_b32 s9, s45, s9
	s_cmp_gt_u32 s54, 15
	s_cselect_b32 s10, s46, s10
	s_cmp_gt_u32 s55, 15
	s_cselect_b32 s11, s47, s11
	s_cmp_gt_u32 s56, 15
	s_cselect_b32 s12, s48, s12
	s_cmp_gt_u32 s57, 15
	s_cselect_b32 s13, s49, s13
	s_or_b32 s42, s6, 0x10000000
	s_or_b32 s43, s7, 0x10000000
	s_or_b32 s44, s8, 0x10000000
	s_or_b32 s45, s9, 0x10000000
	s_or_b32 s46, s10, 0x10000000
	s_or_b32 s47, s11, 0x10000000
	s_or_b32 s48, s12, 0x10000000
	s_or_b32 s49, s13, 0x10000000
	v_cmp_le_u32_e64 s[20:21], s42, v41
	v_cmp_le_u32_e64 s[22:23], s43, v36
	v_cmp_le_u32_e64 s[24:25], s44, v38
	v_cmp_le_u32_e64 s[26:27], s45, v40
	v_cmp_le_u32_e64 s[28:29], s46, v39
	v_cmp_le_u32_e64 s[30:31], s47, v37
;     ...
; #pragma unroll
;     ...
; #pragma unroll
;             for (int qq = 0; qq < 8; ++qq) {
;                 const unsigned cand = thr8[qq] | (1u << bit);
;                 if (__popcll(__ballot(uk8[qq] >= cand)) >= 16) thr8[qq] = cand;
;             }
;         }
	v_cmp_le_u32_e64 s[34:35], s48, v35
	v_cmp_le_u32_e64 s[36:37], s49, v34
	s_bcnt1_i32_b64 s50, s[20:21]
	s_bcnt1_i32_b64 s51, s[22:23]
	s_bcnt1_i32_b64 s52, s[24:25]
	s_bcnt1_i32_b64 s53, s[26:27]
	s_bcnt1_i32_b64 s54, s[28:29]
	s_bcnt1_i32_b64 s55, s[30:31]
	s_bcnt1_i32_b64 s56, s[34:35]
	s_bcnt1_i32_b64 s57, s[36:37]
	s_cmp_gt_u32 s50, 15
	s_cselect_b32 s6, s42, s6
	s_cmp_gt_u32 s51, 15
	s_cselect_b32 s7, s43, s7
	s_cmp_gt_u32 s52, 15
	s_cselect_b32 s8, s44, s8
	s_cmp_gt_u32 s53, 15
	s_cselect_b32 s9, s45, s9
	s_cmp_gt_u32 s54, 15
	s_cselect_b32 s10, s46, s10
	s_cmp_gt_u32 s55, 15
	s_cselect_b32 s11, s47, s11
	s_cmp_gt_u32 s56, 15
	s_cselect_b32 s12, s48, s12
	s_cmp_gt_u32 s57, 15
	s_cselect_b32 s13, s49, s13
	s_or_b32 s42, s6, 0x8000000
	s_or_b32 s43, s7, 0x8000000
	s_or_b32 s44, s8, 0x8000000
	s_or_b32 s45, s9, 0x8000000
	s_or_b32 s46, s10, 0x8000000
	s_or_b32 s47, s11, 0x8000000
	s_or_b32 s48, s12, 0x8000000
	s_or_b32 s49, s13, 0x8000000
	v_cmp_le_u32_e64 s[20:21], s42, v41
	v_cmp_le_u32_e64 s[22:23], s43, v36
	v_cmp_le_u32_e64 s[24:25], s44, v38
	v_cmp_le_u32_e64 s[26:27], s45, v40
	v_cmp_le_u32_e64 s[28:29], s46, v39
	v_cmp_le_u32_e64 s[30:31], s47, v37
	v_cmp_le_u32_e64 s[34:35], s48, v35
	v_cmp_le_u32_e64 s[36:37], s49, v34
	s_bcnt1_i32_b64 s50, s[20:21]
	s_bcnt1_i32_b64 s51, s[22:23]
	s_bcnt1_i32_b64 s52, s[24:25]
	s_bcnt1_i32_b64 s53, s[26:27]
	s_bcnt1_i32_b64 s54, s[28:29]
	s_bcnt1_i32_b64 s55, s[30:31]
	s_bcnt1_i32_b64 s56, s[34:35]
	s_bcnt1_i32_b64 s57, s[36:37]
	s_cmp_gt_u32 s50, 15
	s_cselect_b32 s6, s42, s6
	s_cmp_gt_u32 s51, 15
	s_cselect_b32 s7, s43, s7
	s_cmp_gt_u32 s52, 15
	s_cselect_b32 s8, s44, s8
	s_cmp_gt_u32 s53, 15
	s_cselect_b32 s9, s45, s9
	s_cmp_gt_u32 s54, 15
	s_cselect_b32 s10, s46, s10
	s_cmp_gt_u32 s55, 15
	s_cselect_b32 s11, s47, s11
	s_cmp_gt_u32 s56, 15
	s_cselect_b32 s12, s48, s12
	s_cmp_gt_u32 s57, 15
	s_cselect_b32 s13, s49, s13
	s_or_b32 s42, s6, 0x4000000
	s_or_b32 s43, s7, 0x4000000
	s_or_b32 s44, s8, 0x4000000
	s_or_b32 s45, s9, 0x4000000
	s_or_b32 s46, s10, 0x4000000
	s_or_b32 s47, s11, 0x4000000
	s_or_b32 s48, s12, 0x4000000
	s_or_b32 s49, s13, 0x4000000
	v_cmp_le_u32_e64 s[20:21], s42, v41
	v_cmp_le_u32_e64 s[22:23], s43, v36
	v_cmp_le_u32_e64 s[24:25], s44, v38
	v_cmp_le_u32_e64 s[26:27], s45, v40
	v_cmp_le_u32_e64 s[28:29], s46, v39
	v_cmp_le_u32_e64 s[30:31], s47, v37
	v_cmp_le_u32_e64 s[34:35], s48, v35
	v_cmp_le_u32_e64 s[36:37], s49, v34
	s_bcnt1_i32_b64 s50, s[20:21]
	s_bcnt1_i32_b64 s51, s[22:23]
	s_bcnt1_i32_b64 s52, s[24:25]
	s_bcnt1_i32_b64 s53, s[26:27]
	s_bcnt1_i32_b64 s54, s[28:29]
	s_bcnt1_i32_b64 s55, s[30:31]
	s_bcnt1_i32_b64 s56, s[34:35]
	s_bcnt1_i32_b64 s57, s[36:37]
	s_cmp_gt_u32 s50, 15
	s_cselect_b32 s6, s42, s6
	s_cmp_gt_u32 s51, 15
	s_cselect_b32 s7, s43, s7
	s_cmp_gt_u32 s52, 15
	s_cselect_b32 s8, s44, s8
	s_cmp_gt_u32 s53, 15
	s_cselect_b32 s9, s45, s9
	s_cmp_gt_u32 s54, 15
	s_cselect_b32 s10, s46, s10
	s_cmp_gt_u32 s55, 15
	s_cselect_b32 s11, s47, s11
	s_cmp_gt_u32 s56, 15
	s_cselect_b32 s12, s48, s12
	s_cmp_gt_u32 s57, 15
	s_cselect_b32 s13, s49, s13
	s_or_b32 s42, s6, 0x2000000
	s_or_b32 s43, s7, 0x2000000
	s_or_b32 s44, s8, 0x2000000
	s_or_b32 s45, s9, 0x2000000
	s_or_b32 s46, s10, 0x2000000
	s_or_b32 s47, s11, 0x2000000
	s_or_b32 s48, s12, 0x2000000
	s_or_b32 s49, s13, 0x2000000
	v_cmp_le_u32_e64 s[20:21], s42, v41
	v_cmp_le_u32_e64 s[22:23], s43, v36
	v_cmp_le_u32_e64 s[24:25], s44, v38
	v_cmp_le_u32_e64 s[26:27], s45, v40
	v_cmp_le_u32_e64 s[28:29], s46, v39
	v_cmp_le_u32_e64 s[30:31], s47, v37
	v_cmp_le_u32_e64 s[34:35], s48, v35
	v_cmp_le_u32_e64 s[36:37], s49, v34
	s_bcnt1_i32_b64 s50, s[20:21]
	s_bcnt1_i32_b64 s51, s[22:23]
	s_bcnt1_i32_b64 s52, s[24:25]
	s_bcnt1_i32_b64 s53, s[26:27]
	s_bcnt1_i32_b64 s54, s[28:29]
	s_bcnt1_i32_b64 s55, s[30:31]
	s_bcnt1_i32_b64 s56, s[34:35]
	s_bcnt1_i32_b64 s57, s[36:37]
	s_cmp_gt_u32 s50, 15
	s_cselect_b32 s6, s42, s6
	s_cmp_gt_u32 s51, 15
	s_cselect_b32 s7, s43, s7
	s_cmp_gt_u32 s52, 15
	s_cselect_b32 s8, s44, s8
	s_cmp_gt_u32 s53, 15
	s_cselect_b32 s9, s45, s9
	s_cmp_gt_u32 s54, 15
	s_cselect_b32 s10, s46, s10
	s_cmp_gt_u32 s55, 15
	s_cselect_b32 s11, s47, s11
	s_cmp_gt_u32 s56, 15
	s_cselect_b32 s12, s48, s12
	s_cmp_gt_u32 s57, 15
	s_cselect_b32 s13, s49, s13
	s_or_b32 s42, s6, 0x1000000
	s_or_b32 s43, s7, 0x1000000
	s_or_b32 s44, s8, 0x1000000
	s_or_b32 s45, s9, 0x1000000
	s_or_b32 s46, s10, 0x1000000
	s_or_b32 s47, s11, 0x1000000
	s_or_b32 s48, s12, 0x1000000
	s_or_b32 s49, s13, 0x1000000
	v_cmp_le_u32_e64 s[20:21], s42, v41
	v_cmp_le_u32_e64 s[22:23], s43, v36
	v_cmp_le_u32_e64 s[24:25], s44, v38
	v_cmp_le_u32_e64 s[26:27], s45, v40
	v_cmp_le_u32_e64 s[28:29], s46, v39
	v_cmp_le_u32_e64 s[30:31], s47, v37
	v_cmp_le_u32_e64 s[34:35], s48, v35
	v_cmp_le_u32_e64 s[36:37], s49, v34
	s_bcnt1_i32_b64 s50, s[20:21]
	s_bcnt1_i32_b64 s51, s[22:23]
	s_bcnt1_i32_b64 s52, s[24:25]
	s_bcnt1_i32_b64 s53, s[26:27]
	s_bcnt1_i32_b64 s54, s[28:29]
	s_bcnt1_i32_b64 s55, s[30:31]
	s_bcnt1_i32_b64 s56, s[34:35]
	s_bcnt1_i32_b64 s57, s[36:37]
	s_cmp_gt_u32 s50, 15
	s_cselect_b32 s6, s42, s6
	s_cmp_gt_u32 s51, 15
	s_cselect_b32 s7, s43, s7
	s_cmp_gt_u32 s52, 15
	s_cselect_b32 s8, s44, s8
	s_cmp_gt_u32 s53, 15
	s_cselect_b32 s9, s45, s9
	s_cmp_gt_u32 s54, 15
	s_cselect_b32 s10, s46, s10
	s_cmp_gt_u32 s55, 15
	s_cselect_b32 s11, s47, s11
	s_cmp_gt_u32 s56, 15
	s_cselect_b32 s12, s48, s12
	s_cmp_gt_u32 s57, 15
	s_cselect_b32 s13, s49, s13
	s_or_b32 s42, s6, 0x800000
	s_or_b32 s43, s7, 0x800000
	s_or_b32 s44, s8, 0x800000
	s_or_b32 s45, s9, 0x800000
	s_or_b32 s46, s10, 0x800000
	s_or_b32 s47, s11, 0x800000
	s_or_b32 s48, s12, 0x800000
;     ...
; #pragma unroll
;     ...
; #pragma unroll
;             for (int qq = 0; qq < 8; ++qq) {
;                 const unsigned cand = thr8[qq] | (1u << bit);
;                 if (__popcll(__ballot(uk8[qq] >= cand)) >= 16) thr8[qq] = cand;
;             }
;         }
	s_or_b32 s49, s13, 0x800000
	v_cmp_le_u32_e64 s[20:21], s42, v41
	v_cmp_le_u32_e64 s[22:23], s43, v36
	v_cmp_le_u32_e64 s[24:25], s44, v38
	v_cmp_le_u32_e64 s[26:27], s45, v40
	v_cmp_le_u32_e64 s[28:29], s46, v39
	v_cmp_le_u32_e64 s[30:31], s47, v37
	v_cmp_le_u32_e64 s[34:35], s48, v35
	v_cmp_le_u32_e64 s[36:37], s49, v34
	s_bcnt1_i32_b64 s50, s[20:21]
	s_bcnt1_i32_b64 s51, s[22:23]
	s_bcnt1_i32_b64 s52, s[24:25]
	s_bcnt1_i32_b64 s53, s[26:27]
	s_bcnt1_i32_b64 s54, s[28:29]
	s_bcnt1_i32_b64 s55, s[30:31]
	s_bcnt1_i32_b64 s56, s[34:35]
	s_bcnt1_i32_b64 s57, s[36:37]
	s_cmp_gt_u32 s50, 15
	s_cselect_b32 s6, s42, s6
	s_cmp_gt_u32 s51, 15
	s_cselect_b32 s7, s43, s7
	s_cmp_gt_u32 s52, 15
	s_cselect_b32 s8, s44, s8
	s_cmp_gt_u32 s53, 15
	s_cselect_b32 s9, s45, s9
	s_cmp_gt_u32 s54, 15
	s_cselect_b32 s10, s46, s10
	s_cmp_gt_u32 s55, 15
	s_cselect_b32 s11, s47, s11
	s_cmp_gt_u32 s56, 15
	s_cselect_b32 s12, s48, s12
	s_cmp_gt_u32 s57, 15
	s_cselect_b32 s13, s49, s13
	s_or_b32 s42, s6, 0x400000
	s_or_b32 s43, s7, 0x400000
	s_or_b32 s44, s8, 0x400000
	s_or_b32 s45, s9, 0x400000
	s_or_b32 s46, s10, 0x400000
	s_or_b32 s47, s11, 0x400000
	s_or_b32 s48, s12, 0x400000
	s_or_b32 s49, s13, 0x400000
	v_cmp_le_u32_e64 s[20:21], s42, v41
	v_cmp_le_u32_e64 s[22:23], s43, v36
	v_cmp_le_u32_e64 s[24:25], s44, v38
	v_cmp_le_u32_e64 s[26:27], s45, v40
	v_cmp_le_u32_e64 s[28:29], s46, v39
	v_cmp_le_u32_e64 s[30:31], s47, v37
	v_cmp_le_u32_e64 s[34:35], s48, v35
	v_cmp_le_u32_e64 s[36:37], s49, v34
	s_bcnt1_i32_b64 s50, s[20:21]
	s_bcnt1_i32_b64 s51, s[22:23]
	s_bcnt1_i32_b64 s52, s[24:25]
	s_bcnt1_i32_b64 s53, s[26:27]
	s_bcnt1_i32_b64 s54, s[28:29]
	s_bcnt1_i32_b64 s55, s[30:31]
	s_bcnt1_i32_b64 s56, s[34:35]
	s_bcnt1_i32_b64 s57, s[36:37]
	s_cmp_gt_u32 s50, 15
	s_cselect_b32 s6, s42, s6
	s_cmp_gt_u32 s51, 15
	s_cselect_b32 s7, s43, s7
	s_cmp_gt_u32 s52, 15
	s_cselect_b32 s8, s44, s8
	s_cmp_gt_u32 s53, 15
	s_cselect_b32 s9, s45, s9
	s_cmp_gt_u32 s54, 15
	s_cselect_b32 s10, s46, s10
	s_cmp_gt_u32 s55, 15
	s_cselect_b32 s11, s47, s11
	s_cmp_gt_u32 s56, 15
	s_cselect_b32 s12, s48, s12
	s_cmp_gt_u32 s57, 15
	s_cselect_b32 s13, s49, s13
	s_or_b32 s42, s6, 0x200000
	s_or_b32 s43, s7, 0x200000
	s_or_b32 s44, s8, 0x200000
	s_or_b32 s45, s9, 0x200000
	s_or_b32 s46, s10, 0x200000
	s_or_b32 s47, s11, 0x200000
	s_or_b32 s48, s12, 0x200000
	s_or_b32 s49, s13, 0x200000
	v_cmp_le_u32_e64 s[20:21], s42, v41
	v_cmp_le_u32_e64 s[22:23], s43, v36
	v_cmp_le_u32_e64 s[24:25], s44, v38
	v_cmp_le_u32_e64 s[26:27], s45, v40
	v_cmp_le_u32_e64 s[28:29], s46, v39
	v_cmp_le_u32_e64 s[30:31], s47, v37
	v_cmp_le_u32_e64 s[34:35], s48, v35
	v_cmp_le_u32_e64 s[36:37], s49, v34
	s_bcnt1_i32_b64 s50, s[20:21]
	s_bcnt1_i32_b64 s51, s[22:23]
	s_bcnt1_i32_b64 s52, s[24:25]
	s_bcnt1_i32_b64 s53, s[26:27]
	s_bcnt1_i32_b64 s54, s[28:29]
	s_bcnt1_i32_b64 s55, s[30:31]
	s_bcnt1_i32_b64 s56, s[34:35]
	s_bcnt1_i32_b64 s57, s[36:37]
	s_cmp_gt_u32 s50, 15
	s_cselect_b32 s6, s42, s6
	s_cmp_gt_u32 s51, 15
	s_cselect_b32 s7, s43, s7
	s_cmp_gt_u32 s52, 15
	s_cselect_b32 s8, s44, s8
	s_cmp_gt_u32 s53, 15
	s_cselect_b32 s9, s45, s9
	s_cmp_gt_u32 s54, 15
	s_cselect_b32 s10, s46, s10
	s_cmp_gt_u32 s55, 15
	s_cselect_b32 s11, s47, s11
	s_cmp_gt_u32 s56, 15
	s_cselect_b32 s12, s48, s12
	s_cmp_gt_u32 s57, 15
	s_cselect_b32 s13, s49, s13
	s_or_b32 s42, s6, 0x100000
	s_or_b32 s43, s7, 0x100000
	s_or_b32 s44, s8, 0x100000
	s_or_b32 s45, s9, 0x100000
	s_or_b32 s46, s10, 0x100000
	s_or_b32 s47, s11, 0x100000
	s_or_b32 s48, s12, 0x100000
	s_or_b32 s49, s13, 0x100000
	v_cmp_le_u32_e64 s[20:21], s42, v41
	v_cmp_le_u32_e64 s[22:23], s43, v36
	v_cmp_le_u32_e64 s[24:25], s44, v38
	v_cmp_le_u32_e64 s[26:27], s45, v40
	v_cmp_le_u32_e64 s[28:29], s46, v39
	v_cmp_le_u32_e64 s[30:31], s47, v37
	v_cmp_le_u32_e64 s[34:35], s48, v35
	v_cmp_le_u32_e64 s[36:37], s49, v34
	s_bcnt1_i32_b64 s50, s[20:21]
	s_bcnt1_i32_b64 s51, s[22:23]
	s_bcnt1_i32_b64 s52, s[24:25]
	s_bcnt1_i32_b64 s53, s[26:27]
	s_bcnt1_i32_b64 s54, s[28:29]
	s_bcnt1_i32_b64 s55, s[30:31]
	s_bcnt1_i32_b64 s56, s[34:35]
	s_bcnt1_i32_b64 s57, s[36:37]
	s_cmp_gt_u32 s50, 15
	s_cselect_b32 s6, s42, s6
	s_cmp_gt_u32 s51, 15
	s_cselect_b32 s7, s43, s7
	s_cmp_gt_u32 s52, 15
	s_cselect_b32 s8, s44, s8
	s_cmp_gt_u32 s53, 15
	s_cselect_b32 s9, s45, s9
	s_cmp_gt_u32 s54, 15
	s_cselect_b32 s10, s46, s10
	s_cmp_gt_u32 s55, 15
	s_cselect_b32 s11, s47, s11
	s_cmp_gt_u32 s56, 15
	s_cselect_b32 s12, s48, s12
	s_cmp_gt_u32 s57, 15
	s_cselect_b32 s13, s49, s13
	s_or_b32 s42, s6, 0x80000
	s_or_b32 s43, s7, 0x80000
	s_or_b32 s44, s8, 0x80000
	s_or_b32 s45, s9, 0x80000
	s_or_b32 s46, s10, 0x80000
	s_or_b32 s47, s11, 0x80000
	s_or_b32 s48, s12, 0x80000
	s_or_b32 s49, s13, 0x80000
	v_cmp_le_u32_e64 s[20:21], s42, v41
	v_cmp_le_u32_e64 s[22:23], s43, v36
	v_cmp_le_u32_e64 s[24:25], s44, v38
	v_cmp_le_u32_e64 s[26:27], s45, v40
	v_cmp_le_u32_e64 s[28:29], s46, v39
	v_cmp_le_u32_e64 s[30:31], s47, v37
	v_cmp_le_u32_e64 s[34:35], s48, v35
	v_cmp_le_u32_e64 s[36:37], s49, v34
	s_bcnt1_i32_b64 s50, s[20:21]
	s_bcnt1_i32_b64 s51, s[22:23]
	s_bcnt1_i32_b64 s52, s[24:25]
	s_bcnt1_i32_b64 s53, s[26:27]
	s_bcnt1_i32_b64 s54, s[28:29]
	s_bcnt1_i32_b64 s55, s[30:31]
	s_bcnt1_i32_b64 s56, s[34:35]
	s_bcnt1_i32_b64 s57, s[36:37]
	s_cmp_gt_u32 s50, 15
	s_cselect_b32 s6, s42, s6
	s_cmp_gt_u32 s51, 15
	s_cselect_b32 s7, s43, s7
	s_cmp_gt_u32 s52, 15
	s_cselect_b32 s8, s44, s8
	s_cmp_gt_u32 s53, 15
	s_cselect_b32 s9, s45, s9
	s_cmp_gt_u32 s54, 15
	s_cselect_b32 s10, s46, s10
	s_cmp_gt_u32 s55, 15
	s_cselect_b32 s11, s47, s11
	s_cmp_gt_u32 s56, 15
	s_cselect_b32 s12, s48, s12
	s_cmp_gt_u32 s57, 15
	s_cselect_b32 s13, s49, s13
;     ...
; #pragma unroll
;     ...
; #pragma unroll
;             for (int qq = 0; qq < 8; ++qq) {
;                 const unsigned cand = thr8[qq] | (1u << bit);
;                 if (__popcll(__ballot(uk8[qq] >= cand)) >= 16) thr8[qq] = cand;
;             }
;         }
	s_or_b32 s42, s6, 0x40000
	s_or_b32 s43, s7, 0x40000
	s_or_b32 s44, s8, 0x40000
	s_or_b32 s45, s9, 0x40000
	s_or_b32 s46, s10, 0x40000
	s_or_b32 s47, s11, 0x40000
	s_or_b32 s48, s12, 0x40000
	s_or_b32 s49, s13, 0x40000
	v_cmp_le_u32_e64 s[20:21], s42, v41
	v_cmp_le_u32_e64 s[22:23], s43, v36
	v_cmp_le_u32_e64 s[24:25], s44, v38
	v_cmp_le_u32_e64 s[26:27], s45, v40
	v_cmp_le_u32_e64 s[28:29], s46, v39
	v_cmp_le_u32_e64 s[30:31], s47, v37
	v_cmp_le_u32_e64 s[34:35], s48, v35
	v_cmp_le_u32_e64 s[36:37], s49, v34
	s_bcnt1_i32_b64 s50, s[20:21]
	s_bcnt1_i32_b64 s51, s[22:23]
	s_bcnt1_i32_b64 s52, s[24:25]
	s_bcnt1_i32_b64 s53, s[26:27]
	s_bcnt1_i32_b64 s54, s[28:29]
	s_bcnt1_i32_b64 s55, s[30:31]
	s_bcnt1_i32_b64 s56, s[34:35]
	s_bcnt1_i32_b64 s57, s[36:37]
	s_cmp_gt_u32 s50, 15
	s_cselect_b32 s6, s42, s6
	s_cmp_gt_u32 s51, 15
	s_cselect_b32 s7, s43, s7
	s_cmp_gt_u32 s52, 15
	s_cselect_b32 s8, s44, s8
	s_cmp_gt_u32 s53, 15
	s_cselect_b32 s9, s45, s9
	s_cmp_gt_u32 s54, 15
	s_cselect_b32 s10, s46, s10
	s_cmp_gt_u32 s55, 15
	s_cselect_b32 s11, s47, s11
	s_cmp_gt_u32 s56, 15
	s_cselect_b32 s12, s48, s12
	s_cmp_gt_u32 s57, 15
	s_cselect_b32 s13, s49, s13
	s_or_b32 s42, s6, 0x20000
	s_or_b32 s43, s7, 0x20000
	s_or_b32 s44, s8, 0x20000
	s_or_b32 s45, s9, 0x20000
	s_or_b32 s46, s10, 0x20000
	s_or_b32 s47, s11, 0x20000
	s_or_b32 s48, s12, 0x20000
	s_or_b32 s49, s13, 0x20000
	v_cmp_le_u32_e64 s[20:21], s42, v41
	v_cmp_le_u32_e64 s[22:23], s43, v36
	v_cmp_le_u32_e64 s[24:25], s44, v38
	v_cmp_le_u32_e64 s[26:27], s45, v40
	v_cmp_le_u32_e64 s[28:29], s46, v39
	v_cmp_le_u32_e64 s[30:31], s47, v37
	v_cmp_le_u32_e64 s[34:35], s48, v35
	v_cmp_le_u32_e64 s[36:37], s49, v34
	s_bcnt1_i32_b64 s50, s[20:21]
	s_bcnt1_i32_b64 s51, s[22:23]
	s_bcnt1_i32_b64 s52, s[24:25]
	s_bcnt1_i32_b64 s53, s[26:27]
	s_bcnt1_i32_b64 s54, s[28:29]
	s_bcnt1_i32_b64 s55, s[30:31]
	s_bcnt1_i32_b64 s56, s[34:35]
	s_bcnt1_i32_b64 s57, s[36:37]
	s_cmp_gt_u32 s50, 15
	s_cselect_b32 s6, s42, s6
	s_cmp_gt_u32 s51, 15
	s_cselect_b32 s7, s43, s7
	s_cmp_gt_u32 s52, 15
	s_cselect_b32 s8, s44, s8
	s_cmp_gt_u32 s53, 15
	s_cselect_b32 s9, s45, s9
	s_cmp_gt_u32 s54, 15
	s_cselect_b32 s10, s46, s10
	s_cmp_gt_u32 s55, 15
	s_cselect_b32 s11, s47, s11
	s_cmp_gt_u32 s56, 15
	s_cselect_b32 s12, s48, s12
	s_cmp_gt_u32 s57, 15
	s_cselect_b32 s13, s49, s13
	s_or_b32 s42, s6, 0x10000
	s_or_b32 s43, s7, 0x10000
	s_or_b32 s44, s8, 0x10000
	s_or_b32 s45, s9, 0x10000
	s_or_b32 s46, s10, 0x10000
	s_or_b32 s47, s11, 0x10000
	s_or_b32 s48, s12, 0x10000
	s_or_b32 s49, s13, 0x10000
	v_cmp_le_u32_e64 s[20:21], s42, v41
	v_cmp_le_u32_e64 s[22:23], s43, v36
	v_cmp_le_u32_e64 s[24:25], s44, v38
	v_cmp_le_u32_e64 s[26:27], s45, v40
	v_cmp_le_u32_e64 s[28:29], s46, v39
	v_cmp_le_u32_e64 s[30:31], s47, v37
	v_cmp_le_u32_e64 s[34:35], s48, v35
	v_cmp_le_u32_e64 s[36:37], s49, v34
	s_bcnt1_i32_b64 s50, s[20:21]
	s_bcnt1_i32_b64 s51, s[22:23]
	s_bcnt1_i32_b64 s52, s[24:25]
	s_bcnt1_i32_b64 s53, s[26:27]
	s_bcnt1_i32_b64 s54, s[28:29]
	s_bcnt1_i32_b64 s55, s[30:31]
	s_bcnt1_i32_b64 s56, s[34:35]
	s_bcnt1_i32_b64 s57, s[36:37]
	s_cmp_gt_u32 s50, 15
	s_cselect_b32 s6, s42, s6
	s_cmp_gt_u32 s51, 15
	s_cselect_b32 s7, s43, s7
	s_cmp_gt_u32 s52, 15
	s_cselect_b32 s8, s44, s8
	s_cmp_gt_u32 s53, 15
	s_cselect_b32 s9, s45, s9
	s_cmp_gt_u32 s54, 15
	s_cselect_b32 s10, s46, s10
	s_cmp_gt_u32 s55, 15
	s_cselect_b32 s11, s47, s11
	s_cmp_gt_u32 s56, 15
	s_cselect_b32 s12, s48, s12
	s_cmp_gt_u32 s57, 15
	s_cselect_b32 s13, s49, s13
	s_or_b32 s42, s6, 0x8000
	s_or_b32 s43, s7, 0x8000
	s_or_b32 s44, s8, 0x8000
	s_or_b32 s45, s9, 0x8000
	s_or_b32 s46, s10, 0x8000
	s_or_b32 s47, s11, 0x8000
	s_or_b32 s48, s12, 0x8000
	s_or_b32 s49, s13, 0x8000
	v_cmp_le_u32_e64 s[20:21], s42, v41
	v_cmp_le_u32_e64 s[22:23], s43, v36
	v_cmp_le_u32_e64 s[24:25], s44, v38
	v_cmp_le_u32_e64 s[26:27], s45, v40
	v_cmp_le_u32_e64 s[28:29], s46, v39
	v_cmp_le_u32_e64 s[30:31], s47, v37
	v_cmp_le_u32_e64 s[34:35], s48, v35
	v_cmp_le_u32_e64 s[36:37], s49, v34
	s_bcnt1_i32_b64 s50, s[20:21]
	s_bcnt1_i32_b64 s51, s[22:23]
	s_bcnt1_i32_b64 s52, s[24:25]
	s_bcnt1_i32_b64 s53, s[26:27]
	s_bcnt1_i32_b64 s54, s[28:29]
	s_bcnt1_i32_b64 s55, s[30:31]
	s_bcnt1_i32_b64 s56, s[34:35]
	s_bcnt1_i32_b64 s57, s[36:37]
	s_cmp_gt_u32 s50, 15
	s_cselect_b32 s6, s42, s6
	s_cmp_gt_u32 s51, 15
	s_cselect_b32 s7, s43, s7
	s_cmp_gt_u32 s52, 15
	s_cselect_b32 s8, s44, s8
	s_cmp_gt_u32 s53, 15
	s_cselect_b32 s9, s45, s9
	s_cmp_gt_u32 s54, 15
	s_cselect_b32 s10, s46, s10
	s_cmp_gt_u32 s55, 15
	s_cselect_b32 s11, s47, s11
	s_cmp_gt_u32 s56, 15
	s_cselect_b32 s12, s48, s12
	s_cmp_gt_u32 s57, 15
	s_cselect_b32 s13, s49, s13
	s_or_b32 s42, s6, 0x4000
	s_or_b32 s43, s7, 0x4000
	s_or_b32 s44, s8, 0x4000
	s_or_b32 s45, s9, 0x4000
	s_or_b32 s46, s10, 0x4000
	s_or_b32 s47, s11, 0x4000
	s_or_b32 s48, s12, 0x4000
	s_or_b32 s49, s13, 0x4000
	v_cmp_le_u32_e64 s[20:21], s42, v41
	v_cmp_le_u32_e64 s[22:23], s43, v36
	v_cmp_le_u32_e64 s[24:25], s44, v38
	v_cmp_le_u32_e64 s[26:27], s45, v40
	v_cmp_le_u32_e64 s[28:29], s46, v39
	v_cmp_le_u32_e64 s[30:31], s47, v37
	v_cmp_le_u32_e64 s[34:35], s48, v35
	v_cmp_le_u32_e64 s[36:37], s49, v34
	s_bcnt1_i32_b64 s50, s[20:21]
	s_bcnt1_i32_b64 s51, s[22:23]
	s_bcnt1_i32_b64 s52, s[24:25]
	s_bcnt1_i32_b64 s53, s[26:27]
	s_bcnt1_i32_b64 s54, s[28:29]
	s_bcnt1_i32_b64 s55, s[30:31]
	s_bcnt1_i32_b64 s56, s[34:35]
	s_bcnt1_i32_b64 s57, s[36:37]
	s_cmp_gt_u32 s50, 15
	s_cselect_b32 s6, s42, s6
	s_cmp_gt_u32 s51, 15
	s_cselect_b32 s7, s43, s7
	s_cmp_gt_u32 s52, 15
	s_cselect_b32 s8, s44, s8
	s_cmp_gt_u32 s53, 15
	s_cselect_b32 s9, s45, s9
	s_cmp_gt_u32 s54, 15
	s_cselect_b32 s10, s46, s10
;     ...
; #pragma unroll
;     ...
; #pragma unroll
;             for (int qq = 0; qq < 8; ++qq) {
;                 const unsigned cand = thr8[qq] | (1u << bit);
;                 if (__popcll(__ballot(uk8[qq] >= cand)) >= 16) thr8[qq] = cand;
;             }
;         }
	s_cmp_gt_u32 s55, 15
	s_cselect_b32 s11, s47, s11
	s_cmp_gt_u32 s56, 15
	s_cselect_b32 s12, s48, s12
	s_cmp_gt_u32 s57, 15
	s_cselect_b32 s13, s49, s13
	s_or_b32 s42, s6, 0x2000
	s_or_b32 s43, s7, 0x2000
	s_or_b32 s44, s8, 0x2000
	s_or_b32 s45, s9, 0x2000
	s_or_b32 s46, s10, 0x2000
	s_or_b32 s47, s11, 0x2000
	s_or_b32 s48, s12, 0x2000
	s_or_b32 s49, s13, 0x2000
	v_cmp_le_u32_e64 s[20:21], s42, v41
	v_cmp_le_u32_e64 s[22:23], s43, v36
	v_cmp_le_u32_e64 s[24:25], s44, v38
	v_cmp_le_u32_e64 s[26:27], s45, v40
	v_cmp_le_u32_e64 s[28:29], s46, v39
	v_cmp_le_u32_e64 s[30:31], s47, v37
	v_cmp_le_u32_e64 s[34:35], s48, v35
	v_cmp_le_u32_e64 s[36:37], s49, v34
	s_bcnt1_i32_b64 s50, s[20:21]
	s_bcnt1_i32_b64 s51, s[22:23]
	s_bcnt1_i32_b64 s52, s[24:25]
	s_bcnt1_i32_b64 s53, s[26:27]
	s_bcnt1_i32_b64 s54, s[28:29]
	s_bcnt1_i32_b64 s55, s[30:31]
	s_bcnt1_i32_b64 s56, s[34:35]
	s_bcnt1_i32_b64 s57, s[36:37]
	s_cmp_gt_u32 s50, 15
	s_cselect_b32 s6, s42, s6
	s_cmp_gt_u32 s51, 15
	s_cselect_b32 s7, s43, s7
	s_cmp_gt_u32 s52, 15
	s_cselect_b32 s8, s44, s8
	s_cmp_gt_u32 s53, 15
	s_cselect_b32 s9, s45, s9
	s_cmp_gt_u32 s54, 15
	s_cselect_b32 s10, s46, s10
	s_cmp_gt_u32 s55, 15
	s_cselect_b32 s11, s47, s11
	s_cmp_gt_u32 s56, 15
	s_cselect_b32 s12, s48, s12
	s_cmp_gt_u32 s57, 15
	s_cselect_b32 s13, s49, s13
	s_or_b32 s42, s6, 0x1000
	s_or_b32 s43, s7, 0x1000
	s_or_b32 s44, s8, 0x1000
	s_or_b32 s45, s9, 0x1000
	s_or_b32 s46, s10, 0x1000
	s_or_b32 s47, s11, 0x1000
	s_or_b32 s48, s12, 0x1000
	s_or_b32 s49, s13, 0x1000
	v_cmp_le_u32_e64 s[20:21], s42, v41
	v_cmp_le_u32_e64 s[22:23], s43, v36
	v_cmp_le_u32_e64 s[24:25], s44, v38
	v_cmp_le_u32_e64 s[26:27], s45, v40
	v_cmp_le_u32_e64 s[28:29], s46, v39
	v_cmp_le_u32_e64 s[30:31], s47, v37
	v_cmp_le_u32_e64 s[34:35], s48, v35
	v_cmp_le_u32_e64 s[36:37], s49, v34
	s_bcnt1_i32_b64 s50, s[20:21]
	s_bcnt1_i32_b64 s51, s[22:23]
	s_bcnt1_i32_b64 s52, s[24:25]
	s_bcnt1_i32_b64 s53, s[26:27]
	s_bcnt1_i32_b64 s54, s[28:29]
	s_bcnt1_i32_b64 s55, s[30:31]
	s_bcnt1_i32_b64 s56, s[34:35]
	s_bcnt1_i32_b64 s57, s[36:37]
	s_cmp_gt_u32 s50, 15
	s_cselect_b32 s6, s42, s6
	s_cmp_gt_u32 s51, 15
	s_cselect_b32 s7, s43, s7
	s_cmp_gt_u32 s52, 15
	s_cselect_b32 s8, s44, s8
	s_cmp_gt_u32 s53, 15
	s_cselect_b32 s9, s45, s9
	s_cmp_gt_u32 s54, 15
	s_cselect_b32 s10, s46, s10
	s_cmp_gt_u32 s55, 15
	s_cselect_b32 s11, s47, s11
	s_cmp_gt_u32 s56, 15
	s_cselect_b32 s12, s48, s12
	s_cmp_gt_u32 s57, 15
	s_cselect_b32 s13, s49, s13
	s_or_b32 s42, s6, 0x800
	s_or_b32 s43, s7, 0x800
	s_or_b32 s44, s8, 0x800
	s_or_b32 s45, s9, 0x800
	s_or_b32 s46, s10, 0x800
	s_or_b32 s47, s11, 0x800
	s_or_b32 s48, s12, 0x800
	s_or_b32 s49, s13, 0x800
	v_cmp_le_u32_e64 s[20:21], s42, v41
	v_cmp_le_u32_e64 s[22:23], s43, v36
	v_cmp_le_u32_e64 s[24:25], s44, v38
	v_cmp_le_u32_e64 s[26:27], s45, v40
	v_cmp_le_u32_e64 s[28:29], s46, v39
	v_cmp_le_u32_e64 s[30:31], s47, v37
	v_cmp_le_u32_e64 s[34:35], s48, v35
	v_cmp_le_u32_e64 s[36:37], s49, v34
	s_bcnt1_i32_b64 s50, s[20:21]
	s_bcnt1_i32_b64 s51, s[22:23]
	s_bcnt1_i32_b64 s52, s[24:25]
	s_bcnt1_i32_b64 s53, s[26:27]
	s_bcnt1_i32_b64 s54, s[28:29]
	s_bcnt1_i32_b64 s55, s[30:31]
	s_bcnt1_i32_b64 s56, s[34:35]
	s_bcnt1_i32_b64 s57, s[36:37]
	s_cmp_gt_u32 s50, 15
	s_cselect_b32 s6, s42, s6
	s_cmp_gt_u32 s51, 15
	s_cselect_b32 s7, s43, s7
	s_cmp_gt_u32 s52, 15
	s_cselect_b32 s8, s44, s8
	s_cmp_gt_u32 s53, 15
	s_cselect_b32 s9, s45, s9
	s_cmp_gt_u32 s54, 15
	s_cselect_b32 s10, s46, s10
	s_cmp_gt_u32 s55, 15
	s_cselect_b32 s11, s47, s11
	s_cmp_gt_u32 s56, 15
	s_cselect_b32 s12, s48, s12
	s_cmp_gt_u32 s57, 15
	s_cselect_b32 s13, s49, s13
	s_or_b32 s42, s6, 0x400
	s_or_b32 s43, s7, 0x400
	s_or_b32 s44, s8, 0x400
	s_or_b32 s45, s9, 0x400
	s_or_b32 s46, s10, 0x400
	s_or_b32 s47, s11, 0x400
	s_or_b32 s48, s12, 0x400
	s_or_b32 s49, s13, 0x400
	v_cmp_le_u32_e64 s[20:21], s42, v41
	v_cmp_le_u32_e64 s[22:23], s43, v36
	v_cmp_le_u32_e64 s[24:25], s44, v38
	v_cmp_le_u32_e64 s[26:27], s45, v40
	v_cmp_le_u32_e64 s[28:29], s46, v39
	v_cmp_le_u32_e64 s[30:31], s47, v37
	v_cmp_le_u32_e64 s[34:35], s48, v35
	v_cmp_le_u32_e64 s[36:37], s49, v34
	s_bcnt1_i32_b64 s50, s[20:21]
	s_bcnt1_i32_b64 s51, s[22:23]
	s_bcnt1_i32_b64 s52, s[24:25]
	s_bcnt1_i32_b64 s53, s[26:27]
	s_bcnt1_i32_b64 s54, s[28:29]
	s_bcnt1_i32_b64 s55, s[30:31]
	s_bcnt1_i32_b64 s56, s[34:35]
	s_bcnt1_i32_b64 s57, s[36:37]
	s_cmp_gt_u32 s50, 15
	s_cselect_b32 s6, s42, s6
	s_cmp_gt_u32 s51, 15
	s_cselect_b32 s7, s43, s7
	s_cmp_gt_u32 s52, 15
	s_cselect_b32 s8, s44, s8
	s_cmp_gt_u32 s53, 15
	s_cselect_b32 s9, s45, s9
	s_cmp_gt_u32 s54, 15
	s_cselect_b32 s10, s46, s10
	s_cmp_gt_u32 s55, 15
	s_cselect_b32 s11, s47, s11
	s_cmp_gt_u32 s56, 15
	s_cselect_b32 s12, s48, s12
	s_cmp_gt_u32 s57, 15
	s_cselect_b32 s13, s49, s13
	s_or_b32 s42, s6, 0x200
	s_or_b32 s43, s7, 0x200
	s_or_b32 s44, s8, 0x200
	s_or_b32 s45, s9, 0x200
	s_or_b32 s46, s10, 0x200
	s_or_b32 s47, s11, 0x200
	s_or_b32 s48, s12, 0x200
	s_or_b32 s49, s13, 0x200
	v_cmp_le_u32_e64 s[20:21], s42, v41
	v_cmp_le_u32_e64 s[22:23], s43, v36
	v_cmp_le_u32_e64 s[24:25], s44, v38
	v_cmp_le_u32_e64 s[26:27], s45, v40
	v_cmp_le_u32_e64 s[28:29], s46, v39
	v_cmp_le_u32_e64 s[30:31], s47, v37
	v_cmp_le_u32_e64 s[34:35], s48, v35
	v_cmp_le_u32_e64 s[36:37], s49, v34
	s_bcnt1_i32_b64 s50, s[20:21]
	s_bcnt1_i32_b64 s51, s[22:23]
	s_bcnt1_i32_b64 s52, s[24:25]
	s_bcnt1_i32_b64 s53, s[26:27]
	s_bcnt1_i32_b64 s54, s[28:29]
	s_bcnt1_i32_b64 s55, s[30:31]
	s_bcnt1_i32_b64 s56, s[34:35]
	s_bcnt1_i32_b64 s57, s[36:37]
	s_cmp_gt_u32 s50, 15
	s_cselect_b32 s6, s42, s6
	s_cmp_gt_u32 s51, 15
	s_cselect_b32 s7, s43, s7
	s_cmp_gt_u32 s52, 15
;     ...
; #pragma unroll
;     ...
; #pragma unroll
;             for (int qq = 0; qq < 8; ++qq) {
;                 const unsigned cand = thr8[qq] | (1u << bit);
;                 if (__popcll(__ballot(uk8[qq] >= cand)) >= 16) thr8[qq] = cand;
;             }
;         }
	s_cselect_b32 s8, s44, s8
	s_cmp_gt_u32 s53, 15
	s_cselect_b32 s9, s45, s9
	s_cmp_gt_u32 s54, 15
	s_cselect_b32 s10, s46, s10
	s_cmp_gt_u32 s55, 15
	s_cselect_b32 s11, s47, s11
	s_cmp_gt_u32 s56, 15
	s_cselect_b32 s12, s48, s12
	s_cmp_gt_u32 s57, 15
	s_cselect_b32 s13, s49, s13
	s_or_b32 s42, s6, 0x100
	s_or_b32 s43, s7, 0x100
	s_or_b32 s44, s8, 0x100
	s_or_b32 s45, s9, 0x100
	s_or_b32 s46, s10, 0x100
	s_or_b32 s47, s11, 0x100
	s_or_b32 s48, s12, 0x100
	s_or_b32 s49, s13, 0x100
	v_cmp_le_u32_e64 s[20:21], s42, v41
	v_cmp_le_u32_e64 s[22:23], s43, v36
	v_cmp_le_u32_e64 s[24:25], s44, v38
	v_cmp_le_u32_e64 s[26:27], s45, v40
	v_cmp_le_u32_e64 s[28:29], s46, v39
	v_cmp_le_u32_e64 s[30:31], s47, v37
	v_cmp_le_u32_e64 s[34:35], s48, v35
	v_cmp_le_u32_e64 s[36:37], s49, v34
	s_bcnt1_i32_b64 s50, s[20:21]
	s_bcnt1_i32_b64 s51, s[22:23]
	s_bcnt1_i32_b64 s52, s[24:25]
	s_bcnt1_i32_b64 s53, s[26:27]
	s_bcnt1_i32_b64 s54, s[28:29]
	s_bcnt1_i32_b64 s55, s[30:31]
	s_bcnt1_i32_b64 s56, s[34:35]
	s_bcnt1_i32_b64 s57, s[36:37]
	s_cmp_gt_u32 s50, 15
	s_cselect_b32 s6, s42, s6
	s_cmp_gt_u32 s51, 15
	s_cselect_b32 s7, s43, s7
	s_cmp_gt_u32 s52, 15
	s_cselect_b32 s8, s44, s8
	s_cmp_gt_u32 s53, 15
	s_cselect_b32 s9, s45, s9
	s_cmp_gt_u32 s54, 15
	s_cselect_b32 s10, s46, s10
	s_cmp_gt_u32 s55, 15
	s_cselect_b32 s11, s47, s11
	s_cmp_gt_u32 s56, 15
	s_cselect_b32 s12, s48, s12
	s_cmp_gt_u32 s57, 15
	s_cselect_b32 s13, s49, s13
	s_or_b32 s42, s6, 0x80
	s_or_b32 s43, s7, 0x80
	s_or_b32 s44, s8, 0x80
	s_or_b32 s45, s9, 0x80
	s_or_b32 s46, s10, 0x80
	s_or_b32 s47, s11, 0x80
	s_or_b32 s48, s12, 0x80
	s_or_b32 s49, s13, 0x80
	v_cmp_le_u32_e64 s[20:21], s42, v41
	v_cmp_le_u32_e64 s[22:23], s43, v36
	v_cmp_le_u32_e64 s[24:25], s44, v38
	v_cmp_le_u32_e64 s[26:27], s45, v40
	v_cmp_le_u32_e64 s[28:29], s46, v39
	v_cmp_le_u32_e64 s[30:31], s47, v37
	v_cmp_le_u32_e64 s[34:35], s48, v35
	v_cmp_le_u32_e64 s[36:37], s49, v34
	s_bcnt1_i32_b64 s50, s[20:21]
	s_bcnt1_i32_b64 s51, s[22:23]
	s_bcnt1_i32_b64 s52, s[24:25]
	s_bcnt1_i32_b64 s53, s[26:27]
	s_bcnt1_i32_b64 s54, s[28:29]
	s_bcnt1_i32_b64 s55, s[30:31]
	s_bcnt1_i32_b64 s56, s[34:35]
	s_bcnt1_i32_b64 s57, s[36:37]
	s_cmp_gt_u32 s50, 15
	s_cselect_b32 s6, s42, s6
	s_cmp_gt_u32 s51, 15
	s_cselect_b32 s7, s43, s7
	s_cmp_gt_u32 s52, 15
	s_cselect_b32 s8, s44, s8
	s_cmp_gt_u32 s53, 15
	s_cselect_b32 s9, s45, s9
	s_cmp_gt_u32 s54, 15
	s_cselect_b32 s10, s46, s10
	s_cmp_gt_u32 s55, 15
	s_cselect_b32 s11, s47, s11
	s_cmp_gt_u32 s56, 15
	s_cselect_b32 s12, s48, s12
	s_cmp_gt_u32 s57, 15
	s_cselect_b32 s13, s49, s13
	s_or_b32 s42, s6, 0x40
	s_or_b32 s43, s7, 0x40
	s_or_b32 s44, s8, 0x40
	s_or_b32 s45, s9, 0x40
	s_or_b32 s46, s10, 0x40
	s_or_b32 s47, s11, 0x40
	s_or_b32 s48, s12, 0x40
	s_or_b32 s49, s13, 0x40
	v_cmp_le_u32_e64 s[20:21], s42, v41
	v_cmp_le_u32_e64 s[22:23], s43, v36
	v_cmp_le_u32_e64 s[24:25], s44, v38
	v_cmp_le_u32_e64 s[26:27], s45, v40
	v_cmp_le_u32_e64 s[28:29], s46, v39
	v_cmp_le_u32_e64 s[30:31], s47, v37
	v_cmp_le_u32_e64 s[34:35], s48, v35
	v_cmp_le_u32_e64 s[36:37], s49, v34
	s_bcnt1_i32_b64 s50, s[20:21]
	s_bcnt1_i32_b64 s51, s[22:23]
	s_bcnt1_i32_b64 s52, s[24:25]
	s_bcnt1_i32_b64 s53, s[26:27]
	s_bcnt1_i32_b64 s54, s[28:29]
	s_bcnt1_i32_b64 s55, s[30:31]
	s_bcnt1_i32_b64 s56, s[34:35]
	s_bcnt1_i32_b64 s57, s[36:37]
	s_cmp_gt_u32 s50, 15
	s_cselect_b32 s6, s42, s6
	s_cmp_gt_u32 s51, 15
	s_cselect_b32 s7, s43, s7
	s_cmp_gt_u32 s52, 15
	s_cselect_b32 s8, s44, s8
	s_cmp_gt_u32 s53, 15
	s_cselect_b32 s9, s45, s9
	s_cmp_gt_u32 s54, 15
	s_cselect_b32 s10, s46, s10
	s_cmp_gt_u32 s55, 15
	s_cselect_b32 s11, s47, s11
	s_cmp_gt_u32 s56, 15
	s_cselect_b32 s12, s48, s12
	s_cmp_gt_u32 s57, 15
	s_cselect_b32 s13, s49, s13
	s_or_b32 s42, s6, 0x20
	s_or_b32 s43, s7, 0x20
	s_or_b32 s44, s8, 0x20
	s_or_b32 s45, s9, 0x20
	s_or_b32 s46, s10, 0x20
	s_or_b32 s47, s11, 0x20
	s_or_b32 s48, s12, 0x20
	s_or_b32 s49, s13, 0x20
	v_cmp_le_u32_e64 s[20:21], s42, v41
	v_cmp_le_u32_e64 s[22:23], s43, v36
	v_cmp_le_u32_e64 s[24:25], s44, v38
	v_cmp_le_u32_e64 s[26:27], s45, v40
	v_cmp_le_u32_e64 s[28:29], s46, v39
	v_cmp_le_u32_e64 s[30:31], s47, v37
	v_cmp_le_u32_e64 s[34:35], s48, v35
	v_cmp_le_u32_e64 s[36:37], s49, v34
	s_bcnt1_i32_b64 s50, s[20:21]
	s_bcnt1_i32_b64 s51, s[22:23]
	s_bcnt1_i32_b64 s52, s[24:25]
	s_bcnt1_i32_b64 s53, s[26:27]
	s_bcnt1_i32_b64 s54, s[28:29]
	s_bcnt1_i32_b64 s55, s[30:31]
	s_bcnt1_i32_b64 s56, s[34:35]
	s_bcnt1_i32_b64 s57, s[36:37]
	s_cmp_gt_u32 s50, 15
	s_cselect_b32 s6, s42, s6
	s_cmp_gt_u32 s51, 15
	s_cselect_b32 s7, s43, s7
	s_cmp_gt_u32 s52, 15
	s_cselect_b32 s8, s44, s8
	s_cmp_gt_u32 s53, 15
	s_cselect_b32 s9, s45, s9
	s_cmp_gt_u32 s54, 15
	s_cselect_b32 s10, s46, s10
	s_cmp_gt_u32 s55, 15
	s_cselect_b32 s11, s47, s11
	s_cmp_gt_u32 s56, 15
	s_cselect_b32 s12, s48, s12
	s_cmp_gt_u32 s57, 15
	s_cselect_b32 s13, s49, s13
	s_or_b32 s42, s6, 0x10
	s_or_b32 s43, s7, 0x10
	s_or_b32 s44, s8, 0x10
	s_or_b32 s45, s9, 0x10
	s_or_b32 s46, s10, 0x10
	s_or_b32 s47, s11, 0x10
	s_or_b32 s48, s12, 0x10
	s_or_b32 s49, s13, 0x10
	v_cmp_le_u32_e64 s[20:21], s42, v41
	v_cmp_le_u32_e64 s[22:23], s43, v36
	v_cmp_le_u32_e64 s[24:25], s44, v38
	v_cmp_le_u32_e64 s[26:27], s45, v40
	v_cmp_le_u32_e64 s[28:29], s46, v39
	v_cmp_le_u32_e64 s[30:31], s47, v37
	v_cmp_le_u32_e64 s[34:35], s48, v35
	v_cmp_le_u32_e64 s[36:37], s49, v34
	s_bcnt1_i32_b64 s50, s[20:21]
	s_bcnt1_i32_b64 s51, s[22:23]
	s_bcnt1_i32_b64 s52, s[24:25]
	s_bcnt1_i32_b64 s53, s[26:27]
	s_bcnt1_i32_b64 s54, s[28:29]
	s_bcnt1_i32_b64 s55, s[30:31]
	s_bcnt1_i32_b64 s56, s[34:35]
	s_bcnt1_i32_b64 s57, s[36:37]
	s_cmp_gt_u32 s50, 15
	s_cselect_b32 s6, s42, s6
;     ...
; #pragma unroll
;     ...
; #pragma unroll
;             for (int qq = 0; qq < 8; ++qq) {
;                 const unsigned cand = thr8[qq] | (1u << bit);
;                 if (__popcll(__ballot(uk8[qq] >= cand)) >= 16) thr8[qq] = cand;
;             }
;         }
;         u64 un = 0;
; #pragma unroll
;         for (int qq = 0; qq < 8; ++qq) {
;             const unsigned uk = uk8[qq], thr = thr8[qq];
;             const u64 gtm = __ballot(uk > thr), eqm = __ballot(uk == thr);
;             const int need = 16 - (int)__popcll(gtm);
;             const int below = (int)__builtin_amdgcn_mbcnt_hi((unsigned)(eqm >> 32), __builtin_amdgcn_mbcnt_lo((unsigned)eqm, 0u));
;             const bool sel = ((uk > thr) || (uk == thr && below < need)) && val8[qq];
;             const u64 mask = __ballot(sel);
;             if (lane == 0) SEL[8 * w + qq] = mask;
;             un |= mask;
;         }
;         if (lane == 0) UN[w] = un;
	s_cmp_gt_u32 s51, 15
	s_cselect_b32 s7, s43, s7
	s_cmp_gt_u32 s52, 15
	s_cselect_b32 s8, s44, s8
	s_cmp_gt_u32 s53, 15
	s_cselect_b32 s9, s45, s9
	s_cmp_gt_u32 s54, 15
	s_cselect_b32 s10, s46, s10
	s_cmp_gt_u32 s55, 15
	s_cselect_b32 s11, s47, s11
	s_cmp_gt_u32 s56, 15
	s_cselect_b32 s12, s48, s12
	s_cmp_gt_u32 s57, 15
	s_cselect_b32 s13, s49, s13
	s_or_b32 s42, s6, 0x8
	s_or_b32 s43, s7, 0x8
	s_or_b32 s44, s8, 0x8
	s_or_b32 s45, s9, 0x8
	s_or_b32 s46, s10, 0x8
	s_or_b32 s47, s11, 0x8
	s_or_b32 s48, s12, 0x8
	s_or_b32 s49, s13, 0x8
	v_cmp_le_u32_e64 s[20:21], s42, v41
	v_cmp_le_u32_e64 s[22:23], s43, v36
	v_cmp_le_u32_e64 s[24:25], s44, v38
	v_cmp_le_u32_e64 s[26:27], s45, v40
	v_cmp_le_u32_e64 s[28:29], s46, v39
	v_cmp_le_u32_e64 s[30:31], s47, v37
	v_cmp_le_u32_e64 s[34:35], s48, v35
	v_cmp_le_u32_e64 s[36:37], s49, v34
	s_bcnt1_i32_b64 s50, s[20:21]
	s_bcnt1_i32_b64 s51, s[22:23]
	s_bcnt1_i32_b64 s52, s[24:25]
	s_bcnt1_i32_b64 s53, s[26:27]
	s_bcnt1_i32_b64 s54, s[28:29]
	s_bcnt1_i32_b64 s55, s[30:31]
	s_bcnt1_i32_b64 s56, s[34:35]
	s_bcnt1_i32_b64 s57, s[36:37]
	s_cmp_gt_u32 s50, 15
	s_cselect_b32 s6, s42, s6
	s_cmp_gt_u32 s51, 15
	s_cselect_b32 s7, s43, s7
	s_cmp_gt_u32 s52, 15
	s_cselect_b32 s8, s44, s8
	s_cmp_gt_u32 s53, 15
	s_cselect_b32 s9, s45, s9
	s_cmp_gt_u32 s54, 15
	s_cselect_b32 s10, s46, s10
	s_cmp_gt_u32 s55, 15
	s_cselect_b32 s11, s47, s11
	s_cmp_gt_u32 s56, 15
	s_cselect_b32 s12, s48, s12
	s_cmp_gt_u32 s57, 15
	s_cselect_b32 s13, s49, s13
	s_or_b32 s42, s6, 0x4
	s_or_b32 s43, s7, 0x4
	s_or_b32 s44, s8, 0x4
	s_or_b32 s45, s9, 0x4
	s_or_b32 s46, s10, 0x4
	s_or_b32 s47, s11, 0x4
	s_or_b32 s48, s12, 0x4
	s_or_b32 s49, s13, 0x4
	v_cmp_le_u32_e64 s[20:21], s42, v41
	v_cmp_le_u32_e64 s[22:23], s43, v36
	v_cmp_le_u32_e64 s[24:25], s44, v38
	v_cmp_le_u32_e64 s[26:27], s45, v40
	v_cmp_le_u32_e64 s[28:29], s46, v39
	v_cmp_le_u32_e64 s[30:31], s47, v37
	v_cmp_le_u32_e64 s[34:35], s48, v35
	v_cmp_le_u32_e64 s[36:37], s49, v34
	s_bcnt1_i32_b64 s50, s[20:21]
	s_bcnt1_i32_b64 s51, s[22:23]
	s_bcnt1_i32_b64 s52, s[24:25]
	s_bcnt1_i32_b64 s53, s[26:27]
	s_bcnt1_i32_b64 s54, s[28:29]
	s_bcnt1_i32_b64 s55, s[30:31]
	s_bcnt1_i32_b64 s56, s[34:35]
	s_bcnt1_i32_b64 s57, s[36:37]
	s_cmp_gt_u32 s50, 15
	s_cselect_b32 s6, s42, s6
	s_cmp_gt_u32 s51, 15
	s_cselect_b32 s7, s43, s7
	s_cmp_gt_u32 s52, 15
	s_cselect_b32 s8, s44, s8
	s_cmp_gt_u32 s53, 15
	s_cselect_b32 s9, s45, s9
	s_cmp_gt_u32 s54, 15
	s_cselect_b32 s10, s46, s10
	s_cmp_gt_u32 s55, 15
	s_cselect_b32 s11, s47, s11
	s_cmp_gt_u32 s56, 15
	s_cselect_b32 s12, s48, s12
	s_cmp_gt_u32 s57, 15
	s_cselect_b32 s13, s49, s13
	s_or_b32 s14, s6, 2
	v_cmp_le_u32_e64 s[4:5], s14, v41
	s_bcnt1_i32_b64 s68, s[4:5]
	v_cmp_gt_u64_e64 s[2:3], s[68:69], 15
	s_and_b64 s[2:3], s[2:3], exec
	s_cselect_b32 s6, s14, s6
	s_or_b32 s14, s7, 2
	v_cmp_le_u32_e64 s[4:5], s14, v36
	s_bcnt1_i32_b64 s68, s[4:5]
	v_cmp_gt_u64_e64 s[2:3], s[68:69], 15
	s_and_b64 s[2:3], s[2:3], exec
	s_cselect_b32 s38, s14, s7
	s_or_b32 s7, s8, 2
	v_cmp_le_u32_e64 s[4:5], s7, v38
	s_bcnt1_i32_b64 s68, s[4:5]
	v_cmp_gt_u64_e64 s[2:3], s[68:69], 15
	s_and_b64 s[2:3], s[2:3], exec
	s_cselect_b32 s37, s7, s8
	s_or_b32 s7, s9, 2
	v_cmp_le_u32_e64 s[4:5], s7, v40
	s_bcnt1_i32_b64 s68, s[4:5]
	v_cmp_gt_u64_e64 s[2:3], s[68:69], 15
	s_and_b64 s[2:3], s[2:3], exec
	s_cselect_b32 s35, s7, s9
	s_or_b32 s7, s10, 2
	v_cmp_le_u32_e64 s[4:5], s7, v39
	s_bcnt1_i32_b64 s68, s[4:5]
	v_cmp_gt_u64_e64 s[2:3], s[68:69], 15
	s_and_b64 s[2:3], s[2:3], exec
	s_cselect_b32 s31, s7, s10
	s_or_b32 s7, s11, 2
	v_cmp_le_u32_e64 s[4:5], s7, v37
	s_bcnt1_i32_b64 s68, s[4:5]
	v_cmp_gt_u64_e64 s[2:3], s[68:69], 15
	s_and_b64 s[2:3], s[2:3], exec
	s_cselect_b32 s29, s7, s11
	s_or_b32 s7, s12, 2
	v_cmp_le_u32_e64 s[4:5], s7, v35
	s_bcnt1_i32_b64 s68, s[4:5]
	v_cmp_gt_u64_e64 s[2:3], s[68:69], 15
	s_and_b64 s[2:3], s[2:3], exec
	s_cselect_b32 s27, s7, s12
	s_or_b32 s7, s13, 2
	v_cmp_le_u32_e64 s[4:5], s7, v34
	s_bcnt1_i32_b64 s68, s[4:5]
	v_cmp_gt_u64_e64 s[2:3], s[68:69], 15
	s_and_b64 s[2:3], s[2:3], exec
	s_cselect_b32 s26, s7, s13
	s_or_b32 s7, s6, 1
	v_cmp_le_u32_e64 s[4:5], s7, v41
	s_bcnt1_i32_b64 s68, s[4:5]
	v_cmp_gt_u64_e64 s[2:3], s[68:69], 15
	s_and_b64 s[2:3], s[2:3], exec
	s_cselect_b32 s2, s7, s6
	v_cmp_lt_u32_e64 s[20:21], s2, v41
	v_cmp_eq_u32_e64 s[22:23], s2, v41
	s_bcnt1_i32_b64 s2, s[20:21]
	s_sub_i32 s2, 16, s2
	v_mbcnt_lo_u32_b32 v41, s22, 0
	v_mbcnt_hi_u32_b32 v41, s23, v41
	v_cmp_gt_i32_e64 s[24:25], s2, v41
	s_and_b64 s[2:3], s[22:23], s[24:25]
	s_or_b64 s[2:3], s[20:21], s[2:3]
	s_and_b64 s[2:3], vcc, s[2:3]
	s_or_b32 s41, s38, 1
	s_or_b32 s40, s37, 1
	s_or_b32 s39, s35, 1
	s_or_b32 s36, s31, 1
	s_or_b32 s34, s29, 1
	s_or_b32 s30, s27, 1
	s_or_b32 s28, s26, 1
	v_cndmask_b32_e64 v41, 0, 1, s[2:3]
	v_cmp_le_u32_e64 s[16:17], s41, v36
	v_cmp_le_u32_e64 s[14:15], s40, v38
	v_cmp_le_u32_e64 s[12:13], s39, v40
	v_cmp_le_u32_e64 s[10:11], s36, v39
	v_cmp_le_u32_e64 s[8:9], s34, v37
	v_cmp_le_u32_e64 s[6:7], s30, v35
	v_cmp_le_u32_e64 s[4:5], s28, v34
	v_lshl_add_u32 v42, v83, 3, s75
	v_cmp_ne_u32_e64 s[24:25], 0, v41
	s_and_saveexec_b64 s[2:3], s[18:19]
	s_nop 0
;     ...
; #pragma unroll
;             for (int qq = 0; qq < 8; ++qq) {
;                 const unsigned cand = thr8[qq] | (1u << bit);
;                 if (__popcll(__ballot(uk8[qq] >= cand)) >= 16) thr8[qq] = cand;
;             }
;         }
;         u64 un = 0;
; #pragma unroll
;         for (int qq = 0; qq < 8; ++qq) {
;             const unsigned uk = uk8[qq], thr = thr8[qq];
;             const u64 gtm = __ballot(uk > thr), eqm = __ballot(uk == thr);
;             const int need = 16 - (int)__popcll(gtm);
;             const int below = (int)__builtin_amdgcn_mbcnt_hi((unsigned)(eqm >> 32), __builtin_amdgcn_mbcnt_lo((unsigned)eqm, 0u));
;             const bool sel = ((uk > thr) || (uk == thr && below < need)) && val8[qq];
;             const u64 mask = __ballot(sel);
;             if (lane == 0) SEL[8 * w + qq] = mask;
;             un |= mask;
;         }
;         if (lane == 0) UN[w] = un;
	v_mov_b64_e32 v[44:45], s[24:25]
	ds_write_b64 v42, v[44:45]
	s_or_b64 exec, exec, s[2:3]
	s_bcnt1_i32_b64 s68, s[16:17]
	v_cmp_gt_u64_e64 s[2:3], s[68:69], 15
	s_and_b64 s[2:3], s[2:3], exec
	s_cselect_b32 s2, s41, s38
	v_cmp_lt_u32_e64 s[16:17], s2, v36
	v_cmp_eq_u32_e64 s[20:21], s2, v36
	s_bcnt1_i32_b64 s2, s[16:17]
	s_sub_i32 s2, 16, s2
	v_mbcnt_lo_u32_b32 v36, s20, 0
	v_mbcnt_hi_u32_b32 v36, s21, v36
	v_cmp_gt_i32_e64 s[22:23], s2, v36
	s_and_b64 s[2:3], s[20:21], s[22:23]
	s_or_b64 s[2:3], s[16:17], s[2:3]
	s_and_b64 s[2:3], vcc, s[2:3]
	v_cndmask_b32_e64 v36, 0, 1, s[2:3]
	v_cmp_ne_u32_e64 s[22:23], 0, v36
	s_and_saveexec_b64 s[2:3], s[18:19]
	s_nop 0
	v_mov_b64_e32 v[44:45], s[22:23]
	ds_write_b64 v42, v[44:45] offset:8
	s_or_b64 exec, exec, s[2:3]
	s_bcnt1_i32_b64 s68, s[14:15]
	v_cmp_gt_u64_e64 s[2:3], s[68:69], 15
	s_and_b64 s[2:3], s[2:3], exec
	s_cselect_b32 s2, s40, s37
	v_cmp_lt_u32_e64 s[14:15], s2, v38
	v_cmp_eq_u32_e64 s[16:17], s2, v38
	s_bcnt1_i32_b64 s2, s[14:15]
	s_sub_i32 s2, 16, s2
	v_mbcnt_lo_u32_b32 v36, s16, 0
	v_mbcnt_hi_u32_b32 v36, s17, v36
	v_cmp_gt_i32_e64 s[20:21], s2, v36
	s_and_b64 s[2:3], s[16:17], s[20:21]
	s_or_b64 s[2:3], s[14:15], s[2:3]
	s_and_b64 s[2:3], vcc, s[2:3]
	v_cndmask_b32_e64 v36, 0, 1, s[2:3]
	v_cmp_ne_u32_e64 s[20:21], 0, v36
	s_and_saveexec_b64 s[2:3], s[18:19]
	s_nop 0
	v_mov_b64_e32 v[44:45], s[20:21]
	ds_write_b64 v42, v[44:45] offset:16
	s_or_b64 exec, exec, s[2:3]
	s_bcnt1_i32_b64 s68, s[12:13]
	v_cmp_gt_u64_e64 s[2:3], s[68:69], 15
	s_and_b64 s[2:3], s[2:3], exec
	s_cselect_b32 s2, s39, s35
	v_cmp_lt_u32_e64 s[12:13], s2, v40
	v_cmp_eq_u32_e64 s[14:15], s2, v40
	s_bcnt1_i32_b64 s2, s[12:13]
	s_sub_i32 s2, 16, s2
	v_mbcnt_lo_u32_b32 v36, s14, 0
	v_mbcnt_hi_u32_b32 v36, s15, v36
	v_cmp_gt_i32_e64 s[16:17], s2, v36
	s_and_b64 s[2:3], s[14:15], s[16:17]
	s_or_b64 s[2:3], s[12:13], s[2:3]
	s_and_b64 s[2:3], vcc, s[2:3]
	v_cndmask_b32_e64 v36, 0, 1, s[2:3]
	v_cmp_ne_u32_e64 s[16:17], 0, v36
	s_and_saveexec_b64 s[2:3], s[18:19]
	s_nop 0
	v_mov_b64_e32 v[40:41], s[16:17]
	ds_write_b64 v42, v[40:41] offset:24
	s_or_b64 exec, exec, s[2:3]
	s_bcnt1_i32_b64 s68, s[10:11]
	v_cmp_gt_u64_e64 s[2:3], s[68:69], 15
	s_and_b64 s[2:3], s[2:3], exec
	s_cselect_b32 s2, s36, s31
	v_cmp_lt_u32_e64 s[10:11], s2, v39
	v_cmp_eq_u32_e64 s[12:13], s2, v39
	s_bcnt1_i32_b64 s2, s[10:11]
	s_sub_i32 s2, 16, s2
	v_mbcnt_lo_u32_b32 v36, s12, 0
	v_mbcnt_hi_u32_b32 v36, s13, v36
	v_cmp_gt_i32_e64 s[14:15], s2, v36
	s_and_b64 s[2:3], s[12:13], s[14:15]
	s_or_b64 s[2:3], s[10:11], s[2:3]
	s_and_b64 s[2:3], vcc, s[2:3]
	v_cndmask_b32_e64 v36, 0, 1, s[2:3]
	v_cmp_ne_u32_e64 s[14:15], 0, v36
	s_and_saveexec_b64 s[2:3], s[18:19]
	s_nop 0
	v_mov_b64_e32 v[38:39], s[14:15]
	ds_write_b64 v42, v[38:39] offset:32
	s_or_b64 exec, exec, s[2:3]
	s_bcnt1_i32_b64 s68, s[8:9]
	v_cmp_gt_u64_e64 s[2:3], s[68:69], 15
	s_and_b64 s[2:3], s[2:3], exec
	s_cselect_b32 s2, s34, s29
	v_cmp_lt_u32_e64 s[8:9], s2, v37
	v_cmp_eq_u32_e64 s[10:11], s2, v37
	s_bcnt1_i32_b64 s2, s[8:9]
	s_sub_i32 s2, 16, s2
	v_mbcnt_lo_u32_b32 v36, s10, 0
	v_mbcnt_hi_u32_b32 v36, s11, v36
	v_cmp_gt_i32_e64 s[12:13], s2, v36
	s_and_b64 s[2:3], s[10:11], s[12:13]
	s_or_b64 s[2:3], s[8:9], s[2:3]
	s_and_b64 s[2:3], vcc, s[2:3]
	v_cndmask_b32_e64 v36, 0, 1, s[2:3]
	v_cmp_ne_u32_e64 s[12:13], 0, v36
	s_and_saveexec_b64 s[2:3], s[18:19]
	s_nop 0
	v_mov_b64_e32 v[36:37], s[12:13]
	ds_write_b64 v42, v[36:37] offset:40
	s_or_b64 exec, exec, s[2:3]
	s_bcnt1_i32_b64 s68, s[6:7]
	v_cmp_gt_u64_e64 s[2:3], s[68:69], 15
	s_and_b64 s[2:3], s[2:3], exec
	s_cselect_b32 s2, s30, s27
	v_cmp_lt_u32_e64 s[6:7], s2, v35
	v_cmp_eq_u32_e64 s[8:9], s2, v35
	s_bcnt1_i32_b64 s2, s[6:7]
	s_sub_i32 s2, 16, s2
	v_mbcnt_lo_u32_b32 v35, s8, 0
	v_mbcnt_hi_u32_b32 v35, s9, v35
	v_cmp_gt_i32_e64 s[10:11], s2, v35
	s_and_b64 s[2:3], s[8:9], s[10:11]
	s_or_b64 s[2:3], s[6:7], s[2:3]
	s_and_b64 s[2:3], vcc, s[2:3]
	v_cndmask_b32_e64 v35, 0, 1, s[2:3]
	v_cmp_ne_u32_e64 s[10:11], 0, v35
	s_and_saveexec_b64 s[2:3], s[18:19]
	s_nop 0
	v_mov_b64_e32 v[36:37], s[10:11]
	ds_write_b64 v42, v[36:37] offset:48
	s_or_b64 exec, exec, s[2:3]
	s_bcnt1_i32_b64 s68, s[4:5]
	v_cmp_gt_u64_e64 s[2:3], s[68:69], 15
	s_and_b64 s[2:3], s[2:3], exec
	s_cselect_b32 s2, s28, s26
	v_cmp_lt_u32_e64 s[4:5], s2, v34
	v_cmp_eq_u32_e64 s[6:7], s2, v34
	s_bcnt1_i32_b64 s2, s[4:5]
	s_sub_i32 s2, 16, s2
	v_mbcnt_lo_u32_b32 v34, s6, 0
	v_mbcnt_hi_u32_b32 v34, s7, v34
	v_cmp_gt_i32_e64 s[8:9], s2, v34
	s_and_b64 s[2:3], s[6:7], s[8:9]
	s_or_b64 s[2:3], s[4:5], s[2:3]
	s_and_b64 s[2:3], vcc, s[2:3]
	v_cndmask_b32_e64 v34, 0, 1, s[2:3]
	v_cmp_ne_u32_e64 s[6:7], 0, v34
	s_and_saveexec_b64 s[4:5], s[18:19]
	s_cbranch_execz .LBB0_538
	s_or_b64 s[2:3], s[22:23], s[24:25]
	s_or_b64 s[2:3], s[2:3], s[20:21]
	s_or_b64 s[2:3], s[2:3], s[16:17]
	s_or_b64 s[2:3], s[2:3], s[14:15]
	s_or_b64 s[2:3], s[2:3], s[12:13]
	s_or_b64 s[2:3], s[2:3], s[10:11]
	s_or_b64 s[2:3], s[2:3], s[6:7]
	v_lshl_add_u32 v34, v82, 3, 0
	v_mov_b64_e32 v[36:37], s[6:7]
	v_add_u32_e32 v34, 0x19200, v34
	ds_write_b64 v42, v[36:37] offset:56
	v_mov_b64_e32 v[36:37], s[2:3]
	ds_write_b64 v34, v[36:37]
